# v115 plus nt hint on P0 RMSNorm x-row loads (streamed once)
# speedup vs baseline: 1.0143x; 1.0143x over previous
; #define GAS __attribute__((address_space(1)))
; __device__ __forceinline__ void rms_rows4_to_bf16(const float* xrow, const float* g, bf16* orow, int lane) {
;     const GAS f32x4* xr = (const GAS f32x4*)xrow + lane; const GAS f32x4* gr = (const GAS f32x4*)g + lane;
;     f32x4 v[4][4]; float s[4] = {0.f, 0.f, 0.f, 0.f};
; #pragma unroll
;     for (int r = 0; r < 4; ++r)
; #pragma unroll
;         for (int j = 0; j < 4; ++j) v[r][j] = xr[r * (D / 4) + 64 * j];
; #pragma unroll
;     for (int r = 0; r < 4; ++r)
; #pragma unroll
;         for (int j = 0; j < 4; ++j) s[r] += (v[r][j].x * v[r][j].x + v[r][j].y * v[r][j].y) + (v[r][j].z * v[r][j].z + v[r][j].w * v[r][j].w);
; #pragma unroll
;     for (int r = 0; r < 4; ++r) { const float rs = 1.f / sqrtf(wave_sum(s[r], lane) * (1.f / D) + RMS_EPS);
.LBB0_59:
	global_load_dwordx4 v[14:17], v[76:77], off nt
	global_load_dwordx4 v[10:13], v[76:77], off offset:1024 nt
	global_load_dwordx4 v[6:9], v[76:77], off offset:2048 nt
	global_load_dwordx4 v[2:5], v[76:77], off offset:3072 nt
	v_add_co_u32_e32 v22, vcc, 0x1000, v76
	global_load_dwordx4 v[18:21], v[74:75], off
	s_nop 0
	v_addc_co_u32_e32 v23, vcc, 0, v77, vcc
	v_add_co_u32_e32 v24, vcc, 0x2000, v76
	global_load_dwordx4 v[66:69], v[22:23], off nt
	global_load_dwordx4 v[62:65], v[22:23], off offset:1024 nt
	global_load_dwordx4 v[58:61], v[22:23], off offset:2048 nt
	global_load_dwordx4 v[54:57], v[22:23], off offset:3072 nt
	v_addc_co_u32_e32 v25, vcc, 0, v77, vcc
	global_load_dwordx4 v[50:53], v[24:25], off nt
	global_load_dwordx4 v[46:49], v[24:25], off offset:1024 nt
	global_load_dwordx4 v[42:45], v[24:25], off offset:2048 nt
	global_load_dwordx4 v[38:41], v[24:25], off offset:3072 nt
	v_add_co_u32_e32 v88, vcc, 0x3000, v76
	v_add_co_u32_e64 v80, s[4:5], s2, v78
	s_nop 0
	v_addc_co_u32_e32 v89, vcc, 0, v77, vcc
	global_load_dwordx4 v[34:37], v[88:89], off nt
	global_load_dwordx4 v[30:33], v[88:89], off offset:1024 nt
	global_load_dwordx4 v[26:29], v[88:89], off offset:2048 nt
	global_load_dwordx4 v[22:25], v[88:89], off offset:3072 nt
	v_addc_co_u32_e64 v81, s[4:5], 0, v79, s[4:5]
	s_add_i32 s22, s22, s24
	s_cmp_gt_i32 s22, 0xffff
	v_lshl_add_u64 v[76:77], v[76:77], 0, s[26:27]
	s_waitcnt vmcnt(16)
	v_mul_f32_e32 v88, v15, v15
	v_mul_f32_e32 v89, v17, v17
	s_waitcnt vmcnt(15)
	v_mul_f32_e32 v90, v11, v11
	v_mul_f32_e32 v91, v13, v13
	s_waitcnt vmcnt(14)
	v_mul_f32_e32 v92, v7, v7
	v_mul_f32_e32 v93, v9, v9
	s_waitcnt vmcnt(13)
	v_mul_f32_e32 v94, v3, v3
	v_mul_f32_e32 v95, v5, v5
	v_fmac_f32_e32 v88, v14, v14
	v_fmac_f32_e32 v89, v16, v16
	v_fmac_f32_e32 v90, v10, v10
	v_fmac_f32_e32 v91, v12, v12
	v_fmac_f32_e32 v92, v6, v6
	v_fmac_f32_e32 v93, v8, v8
	v_fmac_f32_e32 v94, v2, v2
	v_fmac_f32_e32 v95, v4, v4
	v_add_f32_e32 v88, v88, v89
	v_add_f32_e32 v89, v90, v91
	v_add_f32_e32 v90, v92, v93
	v_add_f32_e32 v91, v94, v95
	s_waitcnt vmcnt(11)
	v_mul_f32_e32 v92, v67, v67
	v_mul_f32_e32 v93, v69, v69
	s_waitcnt vmcnt(10)
	v_mul_f32_e32 v94, v63, v63
	v_mul_f32_e32 v95, v65, v65
	v_add_f32_e32 v88, v88, v89
	s_waitcnt vmcnt(9)
	v_mul_f32_e32 v96, v59, v59
	v_mul_f32_e32 v97, v61, v61
	v_fmac_f32_e32 v92, v66, v66
	v_fmac_f32_e32 v93, v68, v68
	v_fmac_f32_e32 v94, v62, v62
	v_fmac_f32_e32 v95, v64, v64
	s_waitcnt vmcnt(6)
	v_mul_f32_e32 v101, v47, v47
	v_mul_f32_e32 v102, v49, v49
	v_add_f32_e32 v88, v88, v90
	v_mul_f32_e32 v98, v55, v55
	v_mul_f32_e32 v99, v57, v57
	v_fmac_f32_e32 v96, v58, v58
	v_fmac_f32_e32 v97, v60, v60
	v_mul_f32_e32 v89, v51, v51
	v_mul_f32_e32 v100, v53, v53
	v_add_f32_e32 v90, v92, v93
	v_add_f32_e32 v92, v94, v95
	v_fmac_f32_e32 v101, v46, v46
	v_fmac_f32_e32 v102, v48, v48
	v_add_f32_e32 v88, v88, v91
	v_fmac_f32_e32 v98, v54, v54
	v_fmac_f32_e32 v99, v56, v56
	s_waitcnt vmcnt(5)
	v_mul_f32_e32 v103, v43, v43
	v_mul_f32_e32 v104, v45, v45
	v_add_f32_e32 v93, v96, v97
	v_fmac_f32_e32 v89, v50, v50
	v_fmac_f32_e32 v100, v52, v52
	v_add_f32_e32 v90, v90, v92
	v_add_f32_e32 v91, v101, v102
	ds_bpermute_b32 v101, v82, v88
	s_waitcnt vmcnt(4)
	v_mul_f32_e32 v105, v39, v39
	v_mul_f32_e32 v106, v41, v41
	v_add_f32_e32 v94, v98, v99
	v_fmac_f32_e32 v103, v42, v42
	v_fmac_f32_e32 v104, v44, v44
	s_waitcnt vmcnt(3)
	v_mul_f32_e32 v95, v35, v35
	v_mul_f32_e32 v96, v37, v37
	s_waitcnt vmcnt(2)
	v_mul_f32_e32 v97, v31, v31
	v_mul_f32_e32 v98, v33, v33
	v_add_f32_e32 v89, v89, v100
	v_add_f32_e32 v90, v90, v93
	v_fmac_f32_e32 v105, v38, v38
	v_fmac_f32_e32 v106, v40, v40
	s_waitcnt vmcnt(1)
	v_mul_f32_e32 v99, v27, v27
	v_mul_f32_e32 v107, v29, v29
	v_add_f32_e32 v92, v103, v104
	v_fmac_f32_e32 v95, v34, v34
	v_fmac_f32_e32 v96, v36, v36
	v_fmac_f32_e32 v97, v30, v30
	v_fmac_f32_e32 v98, v32, v32
	v_add_f32_e32 v89, v89, v91
	v_add_f32_e32 v90, v90, v94
	s_waitcnt vmcnt(0)
	v_mul_f32_e32 v108, v23, v23
	v_mul_f32_e32 v109, v25, v25
	v_add_f32_e32 v100, v105, v106
	v_fmac_f32_e32 v99, v26, v26
	v_fmac_f32_e32 v107, v28, v28
	v_add_f32_e32 v91, v95, v96
	v_add_f32_e32 v93, v97, v98
	v_add_f32_e32 v89, v89, v92
	ds_bpermute_b32 v92, v82, v90
	v_fmac_f32_e32 v108, v22, v22
	v_fmac_f32_e32 v109, v24, v24
	v_add_f32_e32 v95, v99, v107
	v_add_f32_e32 v91, v91, v93
	v_add_f32_e32 v89, v89, v100
	v_add_f32_e32 v96, v108, v109
	v_add_f32_e32 v91, v91, v95
	ds_bpermute_b32 v93, v82, v89
	s_waitcnt lgkmcnt(2)
	v_add_f32_e32 v88, v88, v101
	v_add_f32_e32 v91, v91, v96
	ds_bpermute_b32 v95, v83, v88
	ds_bpermute_b32 v94, v82, v91
	s_waitcnt lgkmcnt(3)
	v_add_f32_e32 v90, v90, v92
	ds_bpermute_b32 v92, v83, v90
	s_waitcnt lgkmcnt(3)
	v_add_f32_e32 v89, v89, v93
	ds_bpermute_b32 v93, v83, v89
	s_waitcnt lgkmcnt(3)
	v_add_f32_e32 v88, v88, v95
	s_waitcnt lgkmcnt(2)
	v_add_f32_e32 v91, v91, v94
	ds_bpermute_b32 v94, v84, v88
	s_waitcnt lgkmcnt(2)
	v_add_f32_e32 v90, v90, v92
	ds_bpermute_b32 v92, v84, v90
	s_waitcnt lgkmcnt(2)
	v_add_f32_e32 v89, v89, v93
	ds_bpermute_b32 v93, v84, v89
	s_waitcnt lgkmcnt(2)
	v_add_f32_e32 v88, v88, v94
	ds_bpermute_b32 v94, v85, v88
	s_waitcnt lgkmcnt(2)
	v_add_f32_e32 v90, v90, v92
	ds_bpermute_b32 v92, v85, v90
	s_waitcnt lgkmcnt(2)
	v_add_f32_e32 v89, v89, v93
	ds_bpermute_b32 v93, v85, v89
	s_waitcnt lgkmcnt(2)
	v_add_f32_e32 v88, v88, v94
	ds_bpermute_b32 v94, v86, v88
	s_waitcnt lgkmcnt(2)
	v_add_f32_e32 v90, v90, v92
	ds_bpermute_b32 v92, v86, v90
	s_waitcnt lgkmcnt(2)
	v_add_f32_e32 v89, v89, v93
	ds_bpermute_b32 v93, v86, v89
	s_waitcnt lgkmcnt(2)
	v_add_f32_e32 v88, v88, v94
	ds_bpermute_b32 v94, v87, v88
	s_waitcnt lgkmcnt(2)
; #define GAS __attribute__((address_space(1)))
; __device__ __forceinline__ unsigned pk2(float lo, float hi) { return f2bf(lo) | (f2bf(hi) << 16); }
; __device__ __forceinline__ void rms_rows4_to_bf16(const float* xrow, const float* g, bf16* orow, int lane) {
;     ...
;     for (int r = 0; r < 4; ++r) { const float rs = 1.f / sqrtf(wave_sum(s[r], lane) * (1.f / D) + RMS_EPS);
;         GAS unsigned long long* o8 = (GAS unsigned long long*)(orow + (size_t)r * D) + lane;
; #pragma unroll
;         for (int j = 0; j < 4; ++j) { const f32x4 gg = gr[64 * j];
;             o8[64 * j] = (unsigned long long)pk2(v[r][j].x * rs * gg.x, v[r][j].y * rs * gg.y) | ((unsigned long long)pk2(v[r][j].z * rs * gg.z, v[r][j].w * rs * gg.w) << 32); } }
	v_add_f32_e32 v90, v90, v92
	ds_bpermute_b32 v92, v87, v90
	s_waitcnt lgkmcnt(2)
	v_add_f32_e32 v89, v89, v93
	ds_bpermute_b32 v93, v87, v89
	s_waitcnt lgkmcnt(2)
	v_add_f32_e32 v88, v88, v94
	v_fmamk_f32 v88, v88, 0x3a800000, v71
	v_mul_f32_e32 v94, 0x4f800000, v88
	v_cmp_gt_f32_e32 vcc, s3, v88
	s_waitcnt lgkmcnt(1)
	v_add_f32_e32 v90, v90, v92
	v_fmamk_f32 v90, v90, 0x3a800000, v71
	v_cndmask_b32_e32 v88, v88, v94, vcc
	v_sqrt_f32_e32 v92, v88
	s_waitcnt lgkmcnt(0)
	v_add_f32_e32 v89, v89, v93
	v_mul_f32_e32 v93, 0x4f800000, v90
	v_cmp_gt_f32_e64 s[4:5], s3, v90
	v_fmamk_f32 v89, v89, 0x3a800000, v71
	v_cmp_gt_f32_e64 s[6:7], s3, v89
	v_cndmask_b32_e64 v90, v90, v93, s[4:5]
	v_mul_f32_e32 v93, 0x4f800000, v89
	v_sqrt_f32_e32 v94, v90
	v_cndmask_b32_e64 v89, v89, v93, s[6:7]
	v_add_u32_e32 v95, -1, v92
	v_sqrt_f32_e32 v93, v89
	v_add_u32_e32 v96, 1, v92
	v_fma_f32 v97, -v95, v92, v88
	v_fma_f32 v98, -v96, v92, v88
	v_cmp_ge_f32_e64 s[8:9], 0, v97
	v_add_u32_e32 v97, 1, v94
	v_add_u32_e32 v99, -1, v93
	v_cndmask_b32_e64 v92, v92, v95, s[8:9]
	v_add_u32_e32 v95, -1, v94
	v_cmp_lt_f32_e64 s[8:9], 0, v98
	v_fma_f32 v98, -v97, v94, v90
	v_add_u32_e32 v100, 1, v93
	v_cndmask_b32_e64 v92, v92, v96, s[8:9]
	v_fma_f32 v96, -v95, v94, v90
	v_cmp_ge_f32_e64 s[8:9], 0, v96
	v_mul_f32_e32 v101, 0x37800000, v92
	v_fma_f32 v96, -v100, v93, v89
	v_cndmask_b32_e64 v94, v94, v95, s[8:9]
	v_cmp_lt_f32_e64 s[8:9], 0, v98
	v_fma_f32 v95, -v99, v93, v89
	v_cndmask_b32_e32 v92, v92, v101, vcc
	v_cndmask_b32_e64 v94, v94, v97, s[8:9]
	v_cmp_ge_f32_e32 vcc, 0, v95
	v_cmp_class_f32_e64 s[8:9], v88, v73
	s_nop 0
	v_cndmask_b32_e32 v93, v93, v99, vcc
	v_cmp_lt_f32_e32 vcc, 0, v96
	v_cndmask_b32_e64 v88, v92, v88, s[8:9]
	v_mul_f32_e32 v92, 0x37800000, v94
	v_cndmask_b32_e32 v93, v93, v100, vcc
	v_div_scale_f32 v95, s[8:9], v88, v88, 1.0
	v_cndmask_b32_e64 v92, v94, v92, s[4:5]
	v_cmp_class_f32_e64 s[4:5], v90, v73
	v_mul_f32_e32 v94, 0x37800000, v93
	v_rcp_f32_e32 v97, v95
	v_cndmask_b32_e64 v90, v92, v90, s[4:5]
	v_cndmask_b32_e64 v92, v93, v94, s[6:7]
	v_cmp_class_f32_e64 s[4:5], v89, v73
	v_div_scale_f32 v93, s[6:7], v90, v90, 1.0
	s_nop 0
	v_cndmask_b32_e64 v89, v92, v89, s[4:5]
	v_rcp_f32_e32 v92, v93
	v_div_scale_f32 v98, s[4:5], v89, v89, 1.0
	v_fma_f32 v101, -v95, v97, 1.0
	v_div_scale_f32 v96, vcc, 1.0, v88, 1.0
	v_rcp_f32_e32 v100, v98
	v_fmac_f32_e32 v97, v101, v97
	v_mul_f32_e32 v101, v96, v97
	v_fma_f32 v102, -v93, v92, 1.0
	v_div_scale_f32 v94, s[6:7], 1.0, v90, 1.0
	v_fma_f32 v103, -v95, v101, v96
	v_fmac_f32_e32 v92, v102, v92
	v_fmac_f32_e32 v101, v103, v97
	v_mul_f32_e32 v103, v94, v92
	v_fma_f32 v102, -v98, v100, 1.0
	v_fma_f32 v95, -v95, v101, v96
	v_fma_f32 v96, -v93, v103, v94
	v_div_scale_f32 v99, s[4:5], 1.0, v89, 1.0
	v_fmac_f32_e32 v100, v102, v100
	v_div_fmas_f32 v95, v95, v97, v101
	v_fmac_f32_e32 v103, v96, v92
	v_mul_f32_e32 v102, v99, v100
	v_div_fixup_f32 v88, v95, v88, 1.0
	v_fma_f32 v93, -v93, v103, v94
	s_mov_b64 vcc, s[6:7]
	v_fma_f32 v96, -v98, v102, v99
	v_mul_f32_e32 v14, v14, v88
	v_mul_f32_e32 v16, v16, v88
	v_mul_f32_e32 v94, v2, v88
	v_div_fmas_f32 v2, v93, v92, v103
	v_fmac_f32_e32 v102, v96, v100
	v_mul_f32_e32 v15, v15, v88
	v_mul_f32_e32 v17, v17, v88
	v_mul_f32_e32 v96, v4, v88
	v_mul_f32_e32 v4, v18, v14
	v_mul_f32_e32 v14, v20, v16
	v_div_fixup_f32 v2, v2, v90, 1.0
	v_mul_f32_e32 v10, v10, v88
	v_mul_f32_e32 v11, v11, v88
	v_mul_f32_e32 v12, v12, v88
	v_mul_f32_e32 v13, v13, v88
	v_mul_f32_e32 v6, v6, v88
	v_mul_f32_e32 v7, v7, v88
	v_mul_f32_e32 v8, v8, v88
	v_mul_f32_e32 v9, v9, v88
	v_mul_f32_e32 v95, v3, v88
	v_mul_f32_e32 v88, v5, v88
	v_fma_f32 v3, -v98, v102, v99
	v_mul_f32_e32 v5, v19, v15
	v_mul_f32_e32 v15, v21, v17
	s_mov_b64 vcc, s[4:5]
	v_mul_f32_e32 v16, v66, v2
	v_mul_f32_e32 v17, v67, v2
	v_mul_f32_e32 v18, v68, v2
	v_mul_f32_e32 v19, v69, v2
	v_mul_f32_e32 v20, v62, v2
	v_mul_f32_e32 v21, v63, v2
	v_mul_f32_e32 v62, v64, v2
	v_mul_f32_e32 v63, v65, v2
	v_mul_f32_e32 v58, v58, v2
	v_mul_f32_e32 v59, v59, v2
	v_mul_f32_e32 v60, v60, v2
	v_mul_f32_e32 v61, v61, v2
	v_mul_f32_e32 v54, v54, v2
	v_mul_f32_e32 v55, v55, v2
	v_mul_f32_e32 v56, v56, v2
	v_mul_f32_e32 v57, v57, v2
	v_bfe_u32 v2, v4, 16, 1
	v_bfe_u32 v65, v14, 16, 1
	v_div_fmas_f32 v3, v3, v100, v102
	v_bfe_u32 v64, v5, 16, 1
	v_bfe_u32 v66, v15, 16, 1
	v_add3_u32 v2, v4, v2, s13
	v_add3_u32 v4, v14, v65, s13
	v_div_fixup_f32 v67, v3, v89, 1.0
	v_add3_u32 v3, v5, v64, s13
	v_add3_u32 v5, v15, v66, s13
	v_lshrrev_b32_e32 v2, 16, v2
	v_lshrrev_b32_e32 v4, 16, v4
	v_and_or_b32 v2, v3, s15, v2
	v_and_or_b32 v3, v5, s15, v4
	global_store_dwordx2 v[78:79], v[2:3], off
	global_load_dwordx4 v[2:5], v[74:75], off offset:1024
	v_mul_f32_e32 v14, v50, v67
	v_mul_f32_e32 v50, v52, v67
	v_mul_f32_e32 v15, v51, v67
	v_mul_f32_e32 v51, v53, v67
	v_mul_f32_e32 v46, v46, v67
	v_mul_f32_e32 v47, v47, v67
	s_waitcnt vmcnt(0)
	v_mul_f32_e32 v2, v2, v10
	v_mul_f32_e32 v4, v4, v12
	v_mul_f32_e32 v3, v3, v11
	v_mul_f32_e32 v5, v5, v13
	v_bfe_u32 v10, v2, 16, 1
	v_bfe_u32 v12, v4, 16, 1
	v_bfe_u32 v11, v3, 16, 1
	v_bfe_u32 v13, v5, 16, 1
	v_add3_u32 v2, v2, v10, s13
	v_add3_u32 v4, v4, v12, s13
	v_add3_u32 v3, v3, v11, s13
	v_add3_u32 v5, v5, v13, s13
	v_lshrrev_b32_e32 v2, 16, v2
	v_lshrrev_b32_e32 v4, 16, v4
	v_and_or_b32 v2, v3, s15, v2
	v_and_or_b32 v3, v5, s15, v4
	global_store_dwordx2 v[78:79], v[2:3], off offset:512
	global_load_dwordx4 v[2:5], v[74:75], off offset:2048
	v_mul_f32_e32 v10, v45, v67
	s_waitcnt vmcnt(0)
; #define GAS __attribute__((address_space(1)))
; __device__ __forceinline__ unsigned pk2(float lo, float hi) { return f2bf(lo) | (f2bf(hi) << 16); }
; __device__ __forceinline__ void rms_rows4_to_bf16(const float* xrow, const float* g, bf16* orow, int lane) {
;     ...
;     for (int r = 0; r < 4; ++r) { const float rs = 1.f / sqrtf(wave_sum(s[r], lane) * (1.f / D) + RMS_EPS);
;         GAS unsigned long long* o8 = (GAS unsigned long long*)(orow + (size_t)r * D) + lane;
; #pragma unroll
;         for (int j = 0; j < 4; ++j) { const f32x4 gg = gr[64 * j];
;             o8[64 * j] = (unsigned long long)pk2(v[r][j].x * rs * gg.x, v[r][j].y * rs * gg.y) | ((unsigned long long)pk2(v[r][j].z * rs * gg.z, v[r][j].w * rs * gg.w) << 32); } }
	v_mul_f32_e32 v2, v2, v6
	v_mul_f32_e32 v4, v4, v8
	v_mul_f32_e32 v3, v3, v7
	v_mul_f32_e32 v5, v5, v9
	v_bfe_u32 v6, v2, 16, 1
	v_bfe_u32 v8, v4, 16, 1
	v_bfe_u32 v7, v3, 16, 1
	v_bfe_u32 v9, v5, 16, 1
	v_add3_u32 v2, v2, v6, s13
	v_add3_u32 v4, v4, v8, s13
	v_add3_u32 v3, v3, v7, s13
	v_add3_u32 v5, v5, v9, s13
	v_lshrrev_b32_e32 v2, 16, v2
	v_lshrrev_b32_e32 v4, 16, v4
	v_and_or_b32 v2, v3, s15, v2
	v_and_or_b32 v3, v5, s15, v4
	global_store_dwordx2 v[78:79], v[2:3], off offset:1024
	global_load_dwordx4 v[2:5], v[74:75], off offset:3072
	s_waitcnt vmcnt(0)
	v_mul_f32_e32 v2, v94, v2
	v_mul_f32_e32 v4, v96, v4
	v_mul_f32_e32 v3, v95, v3
	v_mul_f32_e32 v5, v88, v5
	v_bfe_u32 v6, v2, 16, 1
	v_bfe_u32 v8, v4, 16, 1
	v_bfe_u32 v7, v3, 16, 1
	v_bfe_u32 v9, v5, 16, 1
	v_add3_u32 v2, v2, v6, s13
	v_add3_u32 v4, v4, v8, s13
	v_add3_u32 v3, v3, v7, s13
	v_add3_u32 v5, v5, v9, s13
	v_lshrrev_b32_e32 v2, 16, v2
	v_lshrrev_b32_e32 v4, 16, v4
	v_and_or_b32 v2, v3, s15, v2
	v_and_or_b32 v3, v5, s15, v4
	global_store_dwordx2 v[78:79], v[2:3], off offset:1536
	global_load_dwordx4 v[2:5], v[74:75], off
	s_waitcnt vmcnt(0)
	v_mul_f32_e32 v2, v2, v16
	v_mul_f32_e32 v4, v4, v18
	v_mul_f32_e32 v3, v3, v17
	v_mul_f32_e32 v5, v5, v19
	v_bfe_u32 v6, v2, 16, 1
	v_bfe_u32 v8, v4, 16, 1
	v_bfe_u32 v7, v3, 16, 1
	v_bfe_u32 v9, v5, 16, 1
	v_add3_u32 v2, v2, v6, s13
	v_add3_u32 v4, v4, v8, s13
	v_add3_u32 v3, v3, v7, s13
	v_add3_u32 v5, v5, v9, s13
	v_lshrrev_b32_e32 v2, 16, v2
	v_lshrrev_b32_e32 v4, 16, v4
	v_and_or_b32 v2, v3, s15, v2
	v_and_or_b32 v3, v5, s15, v4
	global_store_dwordx2 v[78:79], v[2:3], off offset:2048
	global_load_dwordx4 v[2:5], v[74:75], off offset:1024
	s_waitcnt vmcnt(0)
	v_mul_f32_e32 v2, v2, v20
	v_mul_f32_e32 v4, v4, v62
	v_mul_f32_e32 v3, v3, v21
	v_mul_f32_e32 v5, v5, v63
	v_bfe_u32 v6, v2, 16, 1
	v_bfe_u32 v8, v4, 16, 1
	v_bfe_u32 v7, v3, 16, 1
	v_bfe_u32 v9, v5, 16, 1
	v_add3_u32 v2, v2, v6, s13
	v_add3_u32 v4, v4, v8, s13
	v_add3_u32 v3, v3, v7, s13
	v_add3_u32 v5, v5, v9, s13
	v_lshrrev_b32_e32 v2, 16, v2
	v_lshrrev_b32_e32 v4, 16, v4
	v_and_or_b32 v2, v3, s15, v2
	v_and_or_b32 v3, v5, s15, v4
	global_store_dwordx2 v[78:79], v[2:3], off offset:2560
	global_load_dwordx4 v[2:5], v[74:75], off offset:2048
	s_waitcnt vmcnt(0)
	v_mul_f32_e32 v2, v2, v58
	v_mul_f32_e32 v4, v4, v60
	v_mul_f32_e32 v3, v3, v59
	v_mul_f32_e32 v5, v5, v61
	v_bfe_u32 v6, v2, 16, 1
	v_bfe_u32 v8, v4, 16, 1
	v_bfe_u32 v7, v3, 16, 1
	v_bfe_u32 v9, v5, 16, 1
	v_add3_u32 v2, v2, v6, s13
	v_add3_u32 v4, v4, v8, s13
	v_add3_u32 v3, v3, v7, s13
	v_add3_u32 v5, v5, v9, s13
	v_lshrrev_b32_e32 v2, 16, v2
	v_lshrrev_b32_e32 v4, 16, v4
	v_and_or_b32 v2, v3, s15, v2
	v_and_or_b32 v3, v5, s15, v4
	global_store_dwordx2 v[78:79], v[2:3], off offset:3072
	global_load_dwordx4 v[2:5], v[74:75], off offset:3072
	s_waitcnt vmcnt(0)
	v_mul_f32_e32 v2, v54, v2
	v_mul_f32_e32 v4, v56, v4
	v_mul_f32_e32 v3, v55, v3
	v_mul_f32_e32 v5, v57, v5
	v_bfe_u32 v6, v2, 16, 1
	v_bfe_u32 v8, v4, 16, 1
	v_bfe_u32 v7, v3, 16, 1
	v_bfe_u32 v9, v5, 16, 1
	v_add3_u32 v2, v2, v6, s13
	v_add3_u32 v4, v4, v8, s13
	v_add3_u32 v3, v3, v7, s13
	v_add3_u32 v5, v5, v9, s13
	v_lshrrev_b32_e32 v2, 16, v2
	v_lshrrev_b32_e32 v4, 16, v4
	v_and_or_b32 v2, v3, s15, v2
	v_and_or_b32 v3, v5, s15, v4
	global_store_dwordx2 v[78:79], v[2:3], off offset:3584
	global_load_dwordx4 v[2:5], v[74:75], off
	v_lshl_add_u64 v[78:79], v[78:79], 0, s[28:29]
	s_waitcnt vmcnt(0)
	v_mul_f32_e32 v2, v2, v14
	v_mul_f32_e32 v4, v4, v50
	v_mul_f32_e32 v3, v3, v15
	v_mul_f32_e32 v5, v5, v51
	v_bfe_u32 v6, v2, 16, 1
	v_bfe_u32 v8, v4, 16, 1
	v_bfe_u32 v7, v3, 16, 1
	v_bfe_u32 v9, v5, 16, 1
	v_add3_u32 v2, v2, v6, s13
	v_add3_u32 v4, v4, v8, s13
	v_add3_u32 v3, v3, v7, s13
	v_add3_u32 v5, v5, v9, s13
	v_lshrrev_b32_e32 v2, 16, v2
	v_lshrrev_b32_e32 v4, 16, v4
	v_and_or_b32 v2, v3, s15, v2
	v_and_or_b32 v3, v5, s15, v4
	global_store_dwordx2 v[80:81], v[2:3], off
	global_load_dwordx4 v[2:5], v[74:75], off offset:1024
	v_mul_f32_e32 v6, v48, v67
	v_mul_f32_e32 v7, v49, v67
	s_waitcnt vmcnt(0)
	v_mul_f32_e32 v2, v2, v46
	v_mul_f32_e32 v4, v4, v6
	v_mul_f32_e32 v3, v3, v47
	v_mul_f32_e32 v5, v5, v7
	v_bfe_u32 v6, v2, 16, 1
	v_bfe_u32 v8, v4, 16, 1
	v_bfe_u32 v7, v3, 16, 1
	v_bfe_u32 v9, v5, 16, 1
	v_add3_u32 v2, v2, v6, s13
	v_add3_u32 v4, v4, v8, s13
	v_add3_u32 v3, v3, v7, s13
	v_add3_u32 v5, v5, v9, s13
	v_lshrrev_b32_e32 v2, 16, v2
	v_lshrrev_b32_e32 v4, 16, v4
	v_and_or_b32 v2, v3, s15, v2
	v_and_or_b32 v3, v5, s15, v4
	global_store_dwordx2 v[80:81], v[2:3], off offset:512
	global_load_dwordx4 v[2:5], v[74:75], off offset:2048
	ds_bpermute_b32 v6, v83, v91
	v_mul_f32_e32 v9, v44, v67
	v_mul_f32_e32 v8, v43, v67
	s_waitcnt lgkmcnt(0)
	v_add_f32_e32 v6, v91, v6
	ds_bpermute_b32 v7, v84, v6
	s_waitcnt lgkmcnt(0)
	v_add_f32_e32 v6, v6, v7
	v_mul_f32_e32 v7, v42, v67
	s_waitcnt vmcnt(0)
; #define GAS __attribute__((address_space(1)))
; __device__ __forceinline__ unsigned pk2(float lo, float hi) { return f2bf(lo) | (f2bf(hi) << 16); }
; __device__ __forceinline__ void rms_rows4_to_bf16(const float* xrow, const float* g, bf16* orow, int lane) {
;     ...
;     for (int r = 0; r < 4; ++r) { const float rs = 1.f / sqrtf(wave_sum(s[r], lane) * (1.f / D) + RMS_EPS);
;         GAS unsigned long long* o8 = (GAS unsigned long long*)(orow + (size_t)r * D) + lane;
; #pragma unroll
;         for (int j = 0; j < 4; ++j) { const f32x4 gg = gr[64 * j];
;             o8[64 * j] = (unsigned long long)pk2(v[r][j].x * rs * gg.x, v[r][j].y * rs * gg.y) | ((unsigned long long)pk2(v[r][j].z * rs * gg.z, v[r][j].w * rs * gg.w) << 32); } }
	v_mul_f32_e32 v2, v2, v7
	v_mul_f32_e32 v4, v4, v9
	v_mul_f32_e32 v3, v3, v8
	v_mul_f32_e32 v5, v5, v10
	v_bfe_u32 v7, v2, 16, 1
	v_bfe_u32 v9, v4, 16, 1
	v_bfe_u32 v8, v3, 16, 1
	v_bfe_u32 v10, v5, 16, 1
	v_add3_u32 v2, v2, v7, s13
	v_add3_u32 v4, v4, v9, s13
	v_add3_u32 v3, v3, v8, s13
	v_add3_u32 v5, v5, v10, s13
	v_lshrrev_b32_e32 v2, 16, v2
	v_lshrrev_b32_e32 v4, 16, v4
	v_and_or_b32 v2, v3, s15, v2
	v_and_or_b32 v3, v5, s15, v4
	global_store_dwordx2 v[80:81], v[2:3], off offset:1024
	global_load_dwordx4 v[2:5], v[74:75], off offset:3072
	ds_bpermute_b32 v7, v85, v6
	v_mul_f32_e32 v9, v40, v67
	v_mul_f32_e32 v8, v39, v67
	v_mul_f32_e32 v10, v41, v67
	s_waitcnt lgkmcnt(0)
	v_add_f32_e32 v6, v6, v7
	ds_bpermute_b32 v7, v86, v6
	s_waitcnt lgkmcnt(0)
	v_add_f32_e32 v6, v6, v7
	ds_bpermute_b32 v7, v87, v6
	s_waitcnt lgkmcnt(0)
	v_add_f32_e32 v6, v6, v7
	v_fmamk_f32 v6, v6, 0x3a800000, v71
	v_mul_f32_e32 v7, 0x4f800000, v6
	v_cmp_gt_f32_e32 vcc, s3, v6
	s_waitcnt vmcnt(0)
	v_mul_f32_e32 v4, v9, v4
	v_cndmask_b32_e32 v6, v6, v7, vcc
	v_mul_f32_e32 v7, v38, v67
	v_mul_f32_e32 v2, v7, v2
	v_mul_f32_e32 v3, v8, v3
	v_mul_f32_e32 v5, v10, v5
	v_bfe_u32 v7, v2, 16, 1
	v_bfe_u32 v9, v4, 16, 1
	v_bfe_u32 v8, v3, 16, 1
	v_bfe_u32 v10, v5, 16, 1
	v_add3_u32 v2, v2, v7, s13
	v_add3_u32 v4, v4, v9, s13
	v_add3_u32 v3, v3, v8, s13
	v_add3_u32 v5, v5, v10, s13
	v_lshrrev_b32_e32 v2, 16, v2
	v_lshrrev_b32_e32 v4, 16, v4
	v_and_or_b32 v2, v3, s15, v2
	v_and_or_b32 v3, v5, s15, v4
	global_store_dwordx2 v[80:81], v[2:3], off offset:1536
	global_load_dwordx4 v[2:5], v[74:75], off
	v_sqrt_f32_e32 v7, v6
	s_nop 0
	v_add_u32_e32 v8, -1, v7
	v_add_u32_e32 v9, 1, v7
	v_fma_f32 v10, -v8, v7, v6
	v_fma_f32 v11, -v9, v7, v6
	v_cmp_ge_f32_e64 s[4:5], 0, v10
	s_nop 1
	v_cndmask_b32_e64 v7, v7, v8, s[4:5]
	v_cmp_lt_f32_e64 s[4:5], 0, v11
	s_nop 1
	v_cndmask_b32_e64 v7, v7, v9, s[4:5]
	v_mul_f32_e32 v8, 0x37800000, v7
	v_cndmask_b32_e32 v7, v7, v8, vcc
	v_cmp_class_f32_e32 vcc, v6, v73
	s_nop 1
	v_cndmask_b32_e32 v6, v7, v6, vcc
	v_div_scale_f32 v7, s[4:5], v6, v6, 1.0
	v_rcp_f32_e32 v9, v7
	v_div_scale_f32 v8, vcc, 1.0, v6, 1.0
	v_fma_f32 v10, -v7, v9, 1.0
	v_fmac_f32_e32 v9, v10, v9
	v_mul_f32_e32 v10, v8, v9
	v_fma_f32 v11, -v7, v10, v8
	v_fmac_f32_e32 v10, v11, v9
	v_fma_f32 v7, -v7, v10, v8
	v_div_fmas_f32 v7, v7, v9, v10
	v_div_fixup_f32 v6, v7, v6, 1.0
	v_mul_f32_e32 v7, v34, v6
	v_mul_f32_e32 v9, v36, v6
	v_mul_f32_e32 v8, v35, v6
	v_mul_f32_e32 v10, v37, v6
	s_waitcnt vmcnt(0)
	v_mul_f32_e32 v2, v2, v7
	v_mul_f32_e32 v4, v4, v9
	v_mul_f32_e32 v3, v3, v8
	v_mul_f32_e32 v5, v5, v10
	v_bfe_u32 v7, v2, 16, 1
	v_bfe_u32 v9, v4, 16, 1
	v_bfe_u32 v8, v3, 16, 1
	v_bfe_u32 v10, v5, 16, 1
	v_add3_u32 v2, v2, v7, s13
	v_add3_u32 v4, v4, v9, s13
	v_add3_u32 v3, v3, v8, s13
	v_add3_u32 v5, v5, v10, s13
	v_lshrrev_b32_e32 v2, 16, v2
	v_lshrrev_b32_e32 v4, 16, v4
	v_and_or_b32 v2, v3, s15, v2
	v_and_or_b32 v3, v5, s15, v4
	global_store_dwordx2 v[80:81], v[2:3], off offset:2048
	global_load_dwordx4 v[2:5], v[74:75], off offset:1024
	v_mul_f32_e32 v7, v30, v6
	v_mul_f32_e32 v9, v32, v6
	v_mul_f32_e32 v8, v31, v6
	v_mul_f32_e32 v10, v33, v6
	s_waitcnt vmcnt(0)
	v_mul_f32_e32 v2, v2, v7
	v_mul_f32_e32 v4, v4, v9
	v_mul_f32_e32 v3, v3, v8
	v_mul_f32_e32 v5, v5, v10
	v_bfe_u32 v7, v2, 16, 1
	v_bfe_u32 v9, v4, 16, 1
	v_bfe_u32 v8, v3, 16, 1
	v_bfe_u32 v10, v5, 16, 1
	v_add3_u32 v2, v2, v7, s13
	v_add3_u32 v4, v4, v9, s13
	v_add3_u32 v3, v3, v8, s13
	v_add3_u32 v5, v5, v10, s13
	v_lshrrev_b32_e32 v2, 16, v2
	v_lshrrev_b32_e32 v4, 16, v4
	v_and_or_b32 v2, v3, s15, v2
	v_and_or_b32 v3, v5, s15, v4
	global_store_dwordx2 v[80:81], v[2:3], off offset:2560
	global_load_dwordx4 v[2:5], v[74:75], off offset:2048
	v_mul_f32_e32 v7, v26, v6
	v_mul_f32_e32 v9, v28, v6
	v_mul_f32_e32 v8, v27, v6
	v_mul_f32_e32 v10, v29, v6
	s_waitcnt vmcnt(0)
	v_mul_f32_e32 v2, v2, v7
	v_mul_f32_e32 v4, v4, v9
	v_mul_f32_e32 v3, v3, v8
	v_mul_f32_e32 v5, v5, v10
	v_bfe_u32 v7, v2, 16, 1
	v_bfe_u32 v9, v4, 16, 1
	v_bfe_u32 v8, v3, 16, 1
	v_bfe_u32 v10, v5, 16, 1
	v_add3_u32 v2, v2, v7, s13
	v_add3_u32 v4, v4, v9, s13
	v_add3_u32 v3, v3, v8, s13
	v_add3_u32 v5, v5, v10, s13
	v_lshrrev_b32_e32 v2, 16, v2
	v_lshrrev_b32_e32 v4, 16, v4
	v_and_or_b32 v2, v3, s15, v2
	v_and_or_b32 v3, v5, s15, v4
	global_store_dwordx2 v[80:81], v[2:3], off offset:3072
	global_load_dwordx4 v[2:5], v[74:75], off offset:3072
	v_mul_f32_e32 v7, v22, v6
	v_mul_f32_e32 v9, v24, v6
	v_mul_f32_e32 v8, v23, v6
	v_mul_f32_e32 v6, v25, v6
	s_waitcnt vmcnt(0)
	v_mul_f32_e32 v2, v7, v2
	v_mul_f32_e32 v4, v9, v4
	v_mul_f32_e32 v3, v8, v3
	v_mul_f32_e32 v5, v6, v5
	v_bfe_u32 v6, v2, 16, 1
	v_bfe_u32 v8, v4, 16, 1
	v_bfe_u32 v7, v3, 16, 1
	v_bfe_u32 v9, v5, 16, 1
	v_add3_u32 v2, v2, v6, s13
	v_add3_u32 v4, v4, v8, s13
	v_add3_u32 v3, v3, v7, s13
	v_add3_u32 v5, v5, v9, s13
	v_lshrrev_b32_e32 v2, 16, v2
	v_lshrrev_b32_e32 v4, 16, v4
	v_and_or_b32 v2, v3, s15, v2
	v_and_or_b32 v3, v5, s15, v4
	global_store_dwordx2 v[80:81], v[2:3], off offset:3584
	s_cbranch_scc0 .LBB0_59
